# hot-path straightening: rare causal-mask and rescale blocks moved out of line in fox and selected-branch loops so the common path falls through (3 fewer taken branches per key block)
# baseline (speedup 1.0000x reference)
; template <int MODE> ...
;     ...
;         bf16x8 pk[2][2];
; #pragma unroll
;         for (int nb = 0; nb < 2; ++nb) {
;           f32x16 Sn;
;           if (MODE == M_FOX) {
; #pragma unroll
;             for (int a4 = 0; a4 < 4; ++a4) {
;               const float4 c4 = *(const float4*)(ckt + kb * 32 + 8 * a4 + 4 * h);
;               Sn[4 * a4] = cq[nb] - c4.x; Sn[4 * a4 + 1] = cq[nb] - c4.y; Sn[4 * a4 + 2] = cq[nb] - c4.z; Sn[4 * a4 + 3] = cq[nb] - c4.w;
;             }
;           } else {
; #pragma unroll
;             for (int i = 0; i < 16; ++i) Sn[i] = 0.f;
;           }
; #pragma unroll
;           for (int ks = 0; ks < 4; ++ks) {
;             const bf16x8 a = *(const bf16x8*)(Kt + (kb * 32 + r) * LDK + ks * 16 + 8 * h);
;             Sn = MFMA(a, qf[nb][ks], Sn);
;           }
;           float sv[16];
;           const int t = qpos[nb];
;           bool sb = true;
;           if (MODE == M_SLC) sb = (((selb[nb] >> (key0 >> 6)) & 1ull) != 0ull);
;           if (domask) {
; #pragma unroll
;             for (int i = 0; i < 16; ++i) {
;               const int kk = kbase + (i & 3) + 8 * (i >> 2) + 4 * h;
;               bool valid;
;               if (MODE == M_FOX) valid = (kk <= t);
;               else if (MODE == M_CMP || MODE == M_CMP2) valid = (16 * kk + 31 <= t) && (kk < 255);
;               else if (MODE == M_SLC) valid = sb && (kk <= t);
;               else valid = (kk <= t) && (kk > t - 512);
;               sv[i] = valid ? Sn[i] : -INFINITY;
;             }
;           } else {
; #pragma unroll
;             for (int i = 0; i < 16; ++i) sv[i] = (MODE == M_SLC) ? (sb ? Sn[i] : -INFINITY) : Sn[i];
;           }
;           if (MODE == M_CMP2) {
; #pragma unroll
;             for (int a4 = 0; a4 < 4; ++a4) {
;               float pe[4];
; #pragma unroll
;               for (int e = 0; e < 4; ++e) pe[e] = __builtin_amdgcn_exp2f(sv[4 * a4 + e] - m[nb]) * linv[nb];
;               mainv[nb][a4] = pe[0] + pe[1] + pe[2] + 0.5f * pe[3];
;               spill[nb][a4] = 0.5f * pe[3];
;             }
;           } else {
;             float mx = sv[0];
; #pragma unroll
;             for (int i = 1; i < 16; ++i) mx = fmaxf(mx, sv[i]);
;             mx = fmaxf(mx, shx(mx, lane, 32));
;             if (__any(mx > m[nb] + 8.f)) {
.LBB0_649:
	s_or_b32 s14, s22, s21
	v_cmp_le_i32_e32 vcc, s14, v241
	s_and_saveexec_b64 s[12:13], vcc
	s_cbranch_execz .LBB0_648
	v_or_b32_e32 v2, s22, v240
	v_lshl_add_u32 v112, s22, 2, v0
	v_mad_u32_u24 v132, v2, s76, v15
	ds_read_b128 v[2:5], v112 offset:36960
	ds_read_b128 v[6:9], v112 offset:36928
	ds_read_b128 v[10:13], v112 offset:36896
	ds_read_b128 v[128:131], v112 offset:36864
	ds_read_b128 v[196:199], v132
	ds_read_b128 v[192:195], v132 offset:32
	s_waitcnt lgkmcnt(5)
	v_sub_f32_e32 v127, v80, v5
	v_sub_f32_e32 v126, v80, v4
	v_sub_f32_e32 v125, v80, v3
	v_sub_f32_e32 v124, v80, v2
	s_waitcnt lgkmcnt(4)
	v_sub_f32_e32 v123, v80, v9
	v_sub_f32_e32 v122, v80, v8
	v_sub_f32_e32 v121, v80, v7
	v_sub_f32_e32 v120, v80, v6
	s_waitcnt lgkmcnt(3)
	v_sub_f32_e32 v119, v80, v13
	v_sub_f32_e32 v118, v80, v12
	v_sub_f32_e32 v117, v80, v11
	v_sub_f32_e32 v116, v80, v10
	s_waitcnt lgkmcnt(2)
	v_sub_f32_e32 v115, v80, v131
	v_sub_f32_e32 v114, v80, v130
	v_sub_f32_e32 v113, v80, v129
	v_sub_f32_e32 v112, v80, v128
	ds_read_b128 v[204:207], v132 offset:64
	ds_read_b128 v[200:203], v132 offset:96
	s_waitcnt lgkmcnt(3)
	v_mfma_f32_32x32x16_f16 v[112:127], v[196:199], v[144:147], v[112:127]
	s_or_b32 s0, s14, 31
	v_cmp_gt_i32_e64 s[0:1], s0, v232
	v_or_b32_e32 v213, s14, v244
	v_sub_f32_e32 v143, v82, v5
	v_sub_f32_e32 v142, v82, v4
	v_sub_f32_e32 v141, v82, v3
	v_sub_f32_e32 v140, v82, v2
	s_waitcnt lgkmcnt(2)
	v_mfma_f32_32x32x16_f16 v[112:127], v[192:195], v[148:151], v[112:127]
	v_sub_f32_e32 v139, v82, v9
	v_sub_f32_e32 v138, v82, v8
	v_sub_f32_e32 v137, v82, v7
	v_sub_f32_e32 v136, v82, v6
	s_waitcnt lgkmcnt(1)
	v_mfma_f32_32x32x16_f16 v[112:127], v[204:207], v[152:155], v[112:127]
	v_sub_f32_e32 v135, v82, v13
	v_sub_f32_e32 v134, v82, v12
	v_sub_f32_e32 v133, v82, v11
	v_sub_f32_e32 v132, v82, v10
	s_waitcnt lgkmcnt(0)
	v_mfma_f32_32x32x16_f16 v[112:127], v[200:203], v[156:159], v[112:127]
	v_sub_f32_e32 v131, v82, v131
	v_sub_f32_e32 v130, v82, v130
	v_sub_f32_e32 v129, v82, v129
	v_sub_f32_e32 v128, v82, v128
	s_nop 1
	v_mfma_f32_32x32x16_f16 v[128:143], v[196:199], v[160:163], v[128:143]
	v_mfma_f32_32x32x16_f16 v[128:143], v[192:195], v[164:167], v[128:143]
	v_mfma_f32_32x32x16_f16 v[128:143], v[204:207], v[168:171], v[128:143]
	v_mfma_f32_32x32x16_f16 v[128:143], v[200:203], v[172:175], v[128:143]
	s_and_saveexec_b64 s[14:15], s[0:1]
	s_cbranch_execnz .Lfox_m0
.LBB0_652:
	s_or_b64 exec, exec, s[14:15]
	s_nop 1
	v_max_f32_e32 v2, v113, v113
	v_max_f32_e32 v3, v112, v112
	v_max_f32_e32 v2, v3, v2
	v_max3_f32 v2, v2, v114, v115
	v_max3_f32 v2, v2, v116, v117
	v_max3_f32 v2, v2, v118, v119
	v_max3_f32 v2, v2, v120, v121
	v_max3_f32 v2, v2, v122, v123
	v_max3_f32 v2, v2, v124, v125
	v_max3_f32 v2, v2, v126, v127
	ds_bpermute_b32 v3, v243, v2
	s_and_saveexec_b64 s[14:15], s[0:1]
	s_cbranch_execnz .Lfox_m1
.LBB0_656:
	s_or_b64 exec, exec, s[14:15]
	s_nop 1
	v_max_f32_e32 v4, v129, v129
	v_max_f32_e32 v5, v128, v128
	v_max_f32_e32 v4, v5, v4
	v_max3_f32 v4, v4, v130, v131
	v_max3_f32 v4, v4, v132, v133
	v_max3_f32 v4, v4, v134, v135
	v_max3_f32 v4, v4, v136, v137
	v_max3_f32 v4, v4, v138, v139
	v_max3_f32 v4, v4, v140, v141
	v_max3_f32 v4, v4, v142, v143
	ds_bpermute_b32 v5, v243, v4
	s_waitcnt lgkmcnt(1)
	v_max_f32_e32 v3, v3, v3
	v_max_f32_e32 v2, v2, v3
	v_add_f32_e32 v3, 0x41000000, v219
	v_cmp_gt_f32_e32 vcc, v2, v3
	s_cbranch_vccnz .Lfox_r0

; template <int MODE> ...
;     ...
;           if (domask) {
; #pragma unroll
;             for (int i = 0; i < 16; ++i) {
;               const int kk = kbase + (i & 3) + 8 * (i >> 2) + 4 * h;
;               bool valid;
;               if (MODE == M_FOX) valid = (kk <= t);
;               else if (MODE == M_CMP || MODE == M_CMP2) valid = (16 * kk + 31 <= t) && (kk < 255);
;               else if (MODE == M_SLC) valid = sb && (kk <= t);
;               else valid = (kk <= t) && (kk > t - 512);
;               sv[i] = valid ? Sn[i] : -INFINITY;
;             }
;           } else {
; #pragma unroll
;             for (int i = 0; i < 16; ++i) sv[i] = (MODE == M_SLC) ? (sb ? Sn[i] : -INFINITY) : Sn[i];
;           }
;           if (MODE == M_CMP2) {
; #pragma unroll
;             for (int a4 = 0; a4 < 4; ++a4) {
;               float pe[4];
; #pragma unroll
;               for (int e = 0; e < 4; ++e) pe[e] = __builtin_amdgcn_exp2f(sv[4 * a4 + e] - m[nb]) * linv[nb];
;               mainv[nb][a4] = pe[0] + pe[1] + pe[2] + 0.5f * pe[3];
;               spill[nb][a4] = 0.5f * pe[3];
;             }
;           } else {
;             float mx = sv[0];
; #pragma unroll
;             for (int i = 1; i < 16; ++i) mx = fmaxf(mx, sv[i]);
;             mx = fmaxf(mx, shx(mx, lane, 32));
;             if (__any(mx > m[nb] + 8.f)) {
;               const float mnew = (mx > m[nb] + 8.f) ? mx : m[nb];
;               const float alpha = __builtin_amdgcn_exp2f(m[nb] - mnew);
;               m[nb] = mnew;
;               l[nb] *= alpha;
; #pragma unroll
;               for (int i = 0; i < 16; ++i) { O[0][nb][i] *= alpha; O[1][nb][i] *= alpha; }
;             }
.Lfox_m0:
	v_cmp_le_i32_e32 vcc, v213, v214
	v_or_b32_e32 v2, 2, v213
	s_nop 7
	v_cndmask_b32_e32 v112, v227, v112, vcc
	v_cmp_lt_i32_e32 vcc, v213, v214
	s_nop 1
	v_cndmask_b32_e32 v113, v227, v113, vcc
	v_cmp_le_i32_e32 vcc, v2, v214
	v_or_b32_e32 v2, 3, v213
	s_nop 0
	v_cndmask_b32_e32 v114, v227, v114, vcc
	v_cmp_le_i32_e32 vcc, v2, v214
	v_or_b32_e32 v2, 8, v213
	s_nop 0
	v_cndmask_b32_e32 v115, v227, v115, vcc
	v_cmp_le_i32_e32 vcc, v2, v214
	v_or_b32_e32 v2, 9, v213
	s_nop 0
	v_cndmask_b32_e32 v116, v227, v116, vcc
	v_cmp_le_i32_e32 vcc, v2, v214
	v_or_b32_e32 v2, 10, v213
	s_nop 0
	v_cndmask_b32_e32 v117, v227, v117, vcc
	v_cmp_le_i32_e32 vcc, v2, v214
	v_or_b32_e32 v2, 11, v213
	s_nop 0
	v_cndmask_b32_e32 v118, v227, v118, vcc
	v_cmp_le_i32_e32 vcc, v2, v214
	v_or_b32_e32 v2, 16, v213
	s_nop 0
	v_cndmask_b32_e32 v119, v227, v119, vcc
	v_cmp_le_i32_e32 vcc, v2, v214
	v_or_b32_e32 v2, 17, v213
	s_nop 0
	v_cndmask_b32_e32 v120, v227, v120, vcc
	v_cmp_le_i32_e32 vcc, v2, v214
	v_or_b32_e32 v2, 18, v213
	s_nop 0
	v_cndmask_b32_e32 v121, v227, v121, vcc
	v_cmp_le_i32_e32 vcc, v2, v214
	v_or_b32_e32 v2, 19, v213
	s_nop 0
	v_cndmask_b32_e32 v122, v227, v122, vcc
	v_cmp_le_i32_e32 vcc, v2, v214
	v_or_b32_e32 v2, 24, v213
	s_nop 0
	v_cndmask_b32_e32 v123, v227, v123, vcc
	v_cmp_le_i32_e32 vcc, v2, v214
	v_or_b32_e32 v2, 25, v213
	s_nop 0
	v_cndmask_b32_e32 v124, v227, v124, vcc
	v_cmp_le_i32_e32 vcc, v2, v214
	v_or_b32_e32 v2, 26, v213
	s_nop 0
	v_cndmask_b32_e32 v125, v227, v125, vcc
	v_cmp_le_i32_e32 vcc, v2, v214
	v_or_b32_e32 v2, 27, v213
	s_nop 0
	v_cndmask_b32_e32 v126, v227, v126, vcc
	v_cmp_le_i32_e32 vcc, v2, v214
	s_nop 1
	v_cndmask_b32_e32 v127, v227, v127, vcc
	s_branch .LBB0_652
.Lfox_m1:
	v_cmp_le_i32_e32 vcc, v213, v233
	s_nop 8
	v_cndmask_b32_e32 v128, v227, v128, vcc
	v_cmp_lt_i32_e32 vcc, v213, v233
	s_nop 1
	v_cndmask_b32_e32 v129, v227, v129, vcc
	v_cmp_le_i32_e32 vcc, v213, v247
	s_nop 1
	v_cndmask_b32_e32 v130, v227, v130, vcc
	v_cmp_le_i32_e32 vcc, v213, v248
	s_nop 1
	v_cndmask_b32_e32 v131, v227, v131, vcc
	v_cmp_le_i32_e32 vcc, v213, v249
	s_nop 1
	v_cndmask_b32_e32 v132, v227, v132, vcc
	v_cmp_le_i32_e32 vcc, v213, v250
	s_nop 1
	v_cndmask_b32_e32 v133, v227, v133, vcc
	v_cmp_le_i32_e32 vcc, v213, v218
	s_nop 1
	v_cndmask_b32_e32 v134, v227, v134, vcc
	v_cmp_le_i32_e32 vcc, v213, v216
	s_nop 1
	v_cndmask_b32_e32 v135, v227, v135, vcc
	v_cmp_le_i32_e32 vcc, v213, v217
	s_nop 1
	v_cndmask_b32_e32 v136, v227, v136, vcc
	v_cmp_le_i32_e32 vcc, v213, v228
	s_nop 1
	v_cndmask_b32_e32 v137, v227, v137, vcc
	v_cmp_le_i32_e32 vcc, v213, v229
	s_nop 1
	v_cndmask_b32_e32 v138, v227, v138, vcc
	v_cmp_le_i32_e32 vcc, v213, v230
	s_nop 1
	v_cndmask_b32_e32 v139, v227, v139, vcc
	v_cmp_le_i32_e32 vcc, v213, v231
	s_nop 1
	v_cndmask_b32_e32 v140, v227, v140, vcc
	v_cmp_le_i32_e32 vcc, v213, v223
	s_nop 1
	v_cndmask_b32_e32 v141, v227, v141, vcc
	v_cmp_le_i32_e32 vcc, v213, v226
	s_nop 1
	v_cndmask_b32_e32 v142, v227, v142, vcc
	v_cmp_le_i32_e32 vcc, v213, v221
	s_nop 1
	v_cndmask_b32_e32 v143, v227, v143, vcc
	s_branch .LBB0_656
.Lfox_r0:
	s_nop 0
	v_cndmask_b32_e32 v3, v219, v2, vcc
	v_sub_f32_e32 v2, v219, v3
	v_exp_f32_e32 v2, v2
	v_mov_b32_e32 v219, v3
	v_mul_f32_e32 v208, v208, v2
	v_pk_mul_f32 v[78:79], v[78:79], v[2:3] op_sel_hi:[1,0]
	v_pk_mul_f32 v[76:77], v[76:77], v[2:3] op_sel_hi:[1,0]
	v_pk_mul_f32 v[74:75], v[74:75], v[2:3] op_sel_hi:[1,0]
	v_pk_mul_f32 v[72:73], v[72:73], v[2:3] op_sel_hi:[1,0]
	v_pk_mul_f32 v[70:71], v[70:71], v[2:3] op_sel_hi:[1,0]
	v_pk_mul_f32 v[68:69], v[68:69], v[2:3] op_sel_hi:[1,0]
	v_pk_mul_f32 v[66:67], v[66:67], v[2:3] op_sel_hi:[1,0]
	v_pk_mul_f32 v[64:65], v[64:65], v[2:3] op_sel_hi:[1,0]
	v_pk_mul_f32 v[62:63], v[62:63], v[2:3] op_sel_hi:[1,0]
	v_pk_mul_f32 v[60:61], v[60:61], v[2:3] op_sel_hi:[1,0]
	v_pk_mul_f32 v[58:59], v[58:59], v[2:3] op_sel_hi:[1,0]
	v_pk_mul_f32 v[56:57], v[56:57], v[2:3] op_sel_hi:[1,0]
	v_pk_mul_f32 v[54:55], v[54:55], v[2:3] op_sel_hi:[1,0]
	v_pk_mul_f32 v[52:53], v[52:53], v[2:3] op_sel_hi:[1,0]
	v_pk_mul_f32 v[50:51], v[50:51], v[2:3] op_sel_hi:[1,0]
	v_pk_mul_f32 v[48:49], v[48:49], v[2:3] op_sel_hi:[1,0]
	s_branch .LBB0_654

; template <int MODE> ...
;     ...
;           } else {
;             float mx = sv[0];
; #pragma unroll
;             for (int i = 1; i < 16; ++i) mx = fmaxf(mx, sv[i]);
;             mx = fmaxf(mx, shx(mx, lane, 32));
;             if (__any(mx > m[nb] + 8.f)) {
.LBB0_734:
	v_or_b32_e32 v207, s18, v188
	s_andn2_b64 vcc, exec, s[12:13]
	s_mov_b64 s[12:13], s[4:5]
	s_cbranch_vccz .Lslc_m0
.LBB0_736:
	s_nop 6
	v_max_f32_e32 v96, v81, v81
	v_max_f32_e32 v97, v80, v80
	v_max_f32_e32 v96, v97, v96
	v_max3_f32 v96, v96, v82, v83
	v_max3_f32 v96, v96, v84, v85
	v_max3_f32 v96, v96, v86, v87
	v_max3_f32 v96, v96, v88, v89
	v_max3_f32 v96, v96, v90, v91
	v_cndmask_b32_e64 v95, v227, v111, s[12:13]
	v_max3_f32 v96, v96, v92, v93
	v_max3_f32 v96, v96, v94, v95
	ds_bpermute_b32 v97, v187, v96
	s_waitcnt lgkmcnt(0)
	v_max_f32_e32 v97, v97, v97
	v_max_f32_e32 v96, v96, v97
	v_add_f32_e32 v97, 0x41000000, v15
	v_cmp_gt_f32_e32 vcc, v96, v97
	s_cbranch_vccnz .Lslc_r0

; template <int MODE> ...
;     ...
;           bool sb = true;
;           if (MODE == M_SLC) sb = (((selb[nb] >> (key0 >> 6)) & 1ull) != 0ull);
;           if (domask) {
; #pragma unroll
.LBB0_740:
	s_andn2_b64 vcc, exec, s[10:11]
	s_mov_b64 s[10:11], s[6:7]
	s_cbranch_vccz .Lslc_m1

; template <int MODE> ...
;     ...
;           if (MODE == M_SLC) sb = (((selb[nb] >> (key0 >> 6)) & 1ull) != 0ull);
;           if (domask) {
; #pragma unroll
;             for (int i = 0; i < 16; ++i) {
;               const int kk = kbase + (i & 3) + 8 * (i >> 2) + 4 * h;
;               bool valid;
;               if (MODE == M_FOX) valid = (kk <= t);
;               else if (MODE == M_CMP || MODE == M_CMP2) valid = (16 * kk + 31 <= t) && (kk < 255);
;               else if (MODE == M_SLC) valid = sb && (kk <= t);
;               else valid = (kk <= t) && (kk > t - 512);
;               sv[i] = valid ? Sn[i] : -INFINITY;
;             }
;           } else {
; #pragma unroll
;             for (int i = 0; i < 16; ++i) sv[i] = (MODE == M_SLC) ? (sb ? Sn[i] : -INFINITY) : Sn[i];
;           }
;           if (MODE == M_CMP2) {
; #pragma unroll
;             for (int a4 = 0; a4 < 4; ++a4) {
;               float pe[4];
; #pragma unroll
;               for (int e = 0; e < 4; ++e) pe[e] = __builtin_amdgcn_exp2f(sv[4 * a4 + e] - m[nb]) * linv[nb];
;               mainv[nb][a4] = pe[0] + pe[1] + pe[2] + 0.5f * pe[3];
;               spill[nb][a4] = 0.5f * pe[3];
;             }
;           } else {
;             float mx = sv[0];
; #pragma unroll
;             for (int i = 1; i < 16; ++i) mx = fmaxf(mx, sv[i]);
;             mx = fmaxf(mx, shx(mx, lane, 32));
;             if (__any(mx > m[nb] + 8.f)) {
;               const float mnew = (mx > m[nb] + 8.f) ? mx : m[nb];
;               const float alpha = __builtin_amdgcn_exp2f(m[nb] - mnew);
;               m[nb] = mnew;
;               l[nb] *= alpha;
; #pragma unroll
;               for (int i = 0; i < 16; ++i) { O[0][nb][i] *= alpha; O[1][nb][i] *= alpha; }
;             }
.Lslc_m0:
	v_cmp_le_i32_e32 vcc, v207, v178
	s_and_b64 vcc, s[4:5], vcc
	v_or_b32_e32 v82, 2, v207
	s_nop 3
	v_cndmask_b32_e32 v80, v227, v96, vcc
	v_cmp_lt_i32_e32 vcc, v207, v178
	s_and_b64 vcc, s[4:5], vcc
	v_or_b32_e32 v83, 3, v207
	v_cndmask_b32_e32 v81, v227, v97, vcc
	v_cmp_le_i32_e32 vcc, v82, v178
	s_and_b64 vcc, s[4:5], vcc
	v_or_b32_e32 v84, 8, v207
	v_cndmask_b32_e32 v82, v227, v98, vcc
	v_cmp_le_i32_e32 vcc, v83, v178
	s_and_b64 vcc, s[4:5], vcc
	v_or_b32_e32 v85, 9, v207
	v_cndmask_b32_e32 v83, v227, v99, vcc
	v_cmp_le_i32_e32 vcc, v84, v178
	s_and_b64 vcc, s[4:5], vcc
	v_or_b32_e32 v86, 10, v207
	v_cndmask_b32_e32 v84, v227, v100, vcc
	v_cmp_le_i32_e32 vcc, v85, v178
	s_and_b64 vcc, s[4:5], vcc
	v_or_b32_e32 v87, 11, v207
	v_cndmask_b32_e32 v85, v227, v101, vcc
	v_cmp_le_i32_e32 vcc, v86, v178
	s_and_b64 vcc, s[4:5], vcc
	v_or_b32_e32 v88, 16, v207
	v_cndmask_b32_e32 v86, v227, v102, vcc
	v_cmp_le_i32_e32 vcc, v87, v178
	s_and_b64 vcc, s[4:5], vcc
	v_or_b32_e32 v89, 17, v207
	v_cndmask_b32_e32 v87, v227, v103, vcc
	v_cmp_le_i32_e32 vcc, v88, v178
	s_and_b64 vcc, s[4:5], vcc
	v_or_b32_e32 v90, 18, v207
	v_cndmask_b32_e32 v88, v227, v104, vcc
	v_cmp_le_i32_e32 vcc, v89, v178
	s_and_b64 vcc, s[4:5], vcc
	v_or_b32_e32 v91, 19, v207
	v_cndmask_b32_e32 v89, v227, v105, vcc
	v_cmp_le_i32_e32 vcc, v90, v178
	s_and_b64 vcc, s[4:5], vcc
	v_or_b32_e32 v92, 24, v207
	v_cndmask_b32_e32 v90, v227, v106, vcc
	v_cmp_le_i32_e32 vcc, v91, v178
	s_and_b64 vcc, s[4:5], vcc
	v_or_b32_e32 v93, 25, v207
	v_cndmask_b32_e32 v91, v227, v107, vcc
	v_cmp_le_i32_e32 vcc, v92, v178
	s_and_b64 vcc, s[4:5], vcc
	v_or_b32_e32 v94, 26, v207
	v_cndmask_b32_e32 v92, v227, v108, vcc
	v_cmp_le_i32_e32 vcc, v93, v178
	s_and_b64 vcc, s[4:5], vcc
	v_or_b32_e32 v95, 27, v207
	v_cndmask_b32_e32 v93, v227, v109, vcc
	v_cmp_le_i32_e32 vcc, v94, v178
	s_and_b64 vcc, s[4:5], vcc
	s_andn2_b64 s[18:19], s[4:5], exec
	v_cndmask_b32_e32 v94, v227, v110, vcc
	v_cmp_le_i32_e32 vcc, v95, v178
	s_and_b64 s[12:13], s[4:5], vcc
	s_and_b64 s[12:13], s[12:13], exec
	s_or_b64 s[12:13], s[18:19], s[12:13]
	s_branch .LBB0_736
.Lslc_r0:
	s_nop 0
	v_cndmask_b32_e32 v97, v15, v96, vcc
	v_sub_f32_e32 v15, v15, v97
	v_exp_f32_e32 v96, v15
	v_mov_b32_e32 v15, v97
	v_mul_f32_e32 v14, v14, v96
	v_pk_mul_f32 v[78:79], v[78:79], v[96:97] op_sel_hi:[1,0]
	v_pk_mul_f32 v[76:77], v[76:77], v[96:97] op_sel_hi:[1,0]
	v_pk_mul_f32 v[74:75], v[74:75], v[96:97] op_sel_hi:[1,0]
	v_pk_mul_f32 v[72:73], v[72:73], v[96:97] op_sel_hi:[1,0]
	v_pk_mul_f32 v[70:71], v[70:71], v[96:97] op_sel_hi:[1,0]
	v_pk_mul_f32 v[68:69], v[68:69], v[96:97] op_sel_hi:[1,0]
	v_pk_mul_f32 v[66:67], v[66:67], v[96:97] op_sel_hi:[1,0]
	v_pk_mul_f32 v[64:65], v[64:65], v[96:97] op_sel_hi:[1,0]
	v_pk_mul_f32 v[62:63], v[62:63], v[96:97] op_sel_hi:[1,0]
	v_pk_mul_f32 v[60:61], v[60:61], v[96:97] op_sel_hi:[1,0]
	v_pk_mul_f32 v[58:59], v[58:59], v[96:97] op_sel_hi:[1,0]
	v_pk_mul_f32 v[56:57], v[56:57], v[96:97] op_sel_hi:[1,0]
	v_pk_mul_f32 v[54:55], v[54:55], v[96:97] op_sel_hi:[1,0]
	v_pk_mul_f32 v[52:53], v[52:53], v[96:97] op_sel_hi:[1,0]
	v_pk_mul_f32 v[50:51], v[50:51], v[96:97] op_sel_hi:[1,0]
	v_pk_mul_f32 v[48:49], v[48:49], v[96:97] op_sel_hi:[1,0]
	s_branch .LBB0_738
.Lslc_m1:
	v_cmp_le_i32_e32 vcc, v207, v179
	s_and_b64 vcc, s[6:7], vcc
	s_andn2_b64 s[12:13], s[6:7], exec
	v_cndmask_b32_e32 v80, v227, v96, vcc
	v_cmp_lt_i32_e32 vcc, v207, v179
	s_and_b64 vcc, s[6:7], vcc
	s_nop 0
	v_cndmask_b32_e32 v81, v227, v97, vcc
	v_cmp_le_i32_e32 vcc, v207, v191
	s_and_b64 vcc, s[6:7], vcc
	s_nop 0
	v_cndmask_b32_e32 v82, v227, v98, vcc
	v_cmp_le_i32_e32 vcc, v207, v192
	s_and_b64 vcc, s[6:7], vcc
	s_nop 0
	v_cndmask_b32_e32 v83, v227, v99, vcc
	v_cmp_le_i32_e32 vcc, v207, v193
	s_and_b64 vcc, s[6:7], vcc
	s_nop 0
	v_cndmask_b32_e32 v84, v227, v100, vcc
	v_cmp_le_i32_e32 vcc, v207, v194
	s_and_b64 vcc, s[6:7], vcc
	s_nop 0
	v_cndmask_b32_e32 v85, v227, v101, vcc
	v_cmp_le_i32_e32 vcc, v207, v195
	s_and_b64 vcc, s[6:7], vcc
	s_nop 0
	v_cndmask_b32_e32 v86, v227, v102, vcc
	v_cmp_le_i32_e32 vcc, v207, v196
	s_and_b64 vcc, s[6:7], vcc
	s_nop 0
	v_cndmask_b32_e32 v87, v227, v103, vcc
	v_cmp_le_i32_e32 vcc, v207, v197
	s_and_b64 vcc, s[6:7], vcc
	s_nop 0
	v_cndmask_b32_e32 v88, v227, v104, vcc
	v_cmp_le_i32_e32 vcc, v207, v198
	s_and_b64 vcc, s[6:7], vcc
	s_nop 0
	v_cndmask_b32_e32 v89, v227, v105, vcc
	v_cmp_le_i32_e32 vcc, v207, v199
	s_and_b64 vcc, s[6:7], vcc
	s_nop 0
	v_cndmask_b32_e32 v90, v227, v106, vcc
	v_cmp_le_i32_e32 vcc, v207, v200
	s_and_b64 vcc, s[6:7], vcc
	s_nop 0
	v_cndmask_b32_e32 v91, v227, v107, vcc
	v_cmp_le_i32_e32 vcc, v207, v201
	s_and_b64 vcc, s[6:7], vcc
	s_nop 0
	v_cndmask_b32_e32 v92, v227, v108, vcc
	v_cmp_le_i32_e32 vcc, v207, v202
	s_and_b64 vcc, s[6:7], vcc
	s_nop 0
	v_cndmask_b32_e32 v93, v227, v109, vcc
	v_cmp_le_i32_e32 vcc, v207, v203
	s_and_b64 vcc, s[6:7], vcc
	s_nop 0
	v_cndmask_b32_e32 v94, v227, v110, vcc
	v_cmp_le_i32_e32 vcc, v207, v204
	s_and_b64 s[10:11], s[6:7], vcc
	s_and_b64 s[10:11], s[10:11], exec
	s_or_b64 s[10:11], s[12:13], s[10:11]
	s_branch .LBB0_742
